# batch-per-XCC placement (attention units and forget-gate rows dealt by workgroup&7 like the GEMM row tiles) + XCC-local barriers (no L2 write-back, no cross-XCC stage) at W_in->attention, W_out->gate/
# speedup vs baseline: 1.0170x; 1.0170x over previous
; __device__ __forceinline__ void attn_phase(const Args& a, int l, LAS unsigned char* lds, const int tid, const int rep) {
;     ...
;     for (;;) {
;         if (tid == 0) *nextu = atomicAdd(ctr, 1u);
;         __syncthreads();
;         const unsigned i = *nextu;
;         __syncthreads();
;         if (i >= 1024u) break;
;         if (i < 512u) {
;             const int qb = 15 - (int)(i >> 5), bh = (int)(i & 31), b = bh >> 2, h = bh & 3;
;             const float slope2 = exp2f(-2.0f * (float)(h + 1)) * LOG2E;
;             attn_unit<128, 2>(lds, U, MIX, logf, b, h, qb, lam, slope2, gn, 1.0f - lam_init, tid);
;         } else {
;             const int j = (int)i - 512, qb = 7 - (j >> 6), bh = j & 63, b = bh >> 3, h = bh & 7;
;             attn_unit<64, 1>(lds, U, MIX, logf, b, h, qb, 0.f, 0.f, gn, 1.f, tid);
;         }
.LBB0_178:
	v_readlane_b32 s20, v251, 11
	s_cmp_lg_u32 s20, 0x4000
	s_cbranch_scc1 .Lat_dyn
	v_readlane_b32 s20, v255, 20
	v_readlane_b32 s36, v249, 0
	s_add_i32 s27, s20, 1
	s_nop 1
	v_writelane_b32 v255, s27, 20
	s_and_b32 s30, s36, 7
	s_cmp_lt_u32 s20, 2
	s_cbranch_scc0 .Lat_pfx
	s_lshl_b32 s30, s30, 2
	s_bfe_u32 s31, s36, 0x20003
	s_or_b32 s30, s30, s31
	s_andn2_b32 s36, s36, 31
	s_branch .Lat_pdone
.Lat_pfx:
	s_lshl_b32 s30, s30, 3
	s_bfe_u32 s31, s36, 0x30003
	s_or_b32 s30, s30, s31
	s_andn2_b32 s36, s36, 63
.Lat_pdone:
	s_or_b32 s36, s36, s30
	s_cmp_eq_u32 s20, 1
	s_cselect_b32 s27, 0x1e0, 0
	s_cmp_eq_u32 s20, 2
	s_cselect_b32 s27, 0x200, s27
	s_cmp_eq_u32 s20, 3
	s_cselect_b32 s27, 0x3c0, s27
	s_xor_b32 s27, s27, s36
	s_cmp_gt_u32 s20, 3
	s_cselect_b32 s27, 0x400, s27
	v_mov_b32_e32 v0, s27
	s_mov_b64 s[30:31], -1
	s_branch .Lat_disp

; __device__ __forceinline__ void fg_tail(const Args& a, int l, LAS unsigned char* lds, const int tid) {
;     ...
;         const f32x4* wsrc = (const f32x4*)((const float*)(ws + WS_WFGT) + (size_t)l * 8192);
; #pragma unroll
;         for (int i = 0; i < 4; ++i) { const int idx = tid + 512 * i, j = idx >> 8, k4 = idx & 255, ln = k4 >> 2, q = k4 & 3; wl[(j * 4 + q) * 64 + ln] = wsrc[idx]; }
;     }
;     __syncthreads();
;     const bf16_t* H = (const bf16_t*)(ws + WS_H); const float* rowss = (const float*)(ws + WS_ROWSS) + (size_t)(2 * l) * MT * 4;
;     const float* mod = (const float*)(ws + WS_MOD) + (size_t)l * 8 * MODW; float* logf = (float*)(ws + WS_LOGF);
;     const float bfv = a.in[7][l * 8 + (lane >> 3)];
;     for (int chunk = blockIdx.x * 8 + wid; chunk * 8 < MT; chunk += gridDim.x * 8) {
;         const int rowc = chunk * 8, b = rowc >> 11;
;         f32x4 sh[4];
; #pragma unroll
;         for (int q = 0; q < 4; ++q) sh[q] = *(const f32x4*)(mod + (size_t)b * MODW + 16 * lane + 4 * q);
; #pragma unroll 1
;         for (int jb = 0; jb < 8; jb += 4) {
;             f32x4 rs4v[4]; u32x4 w0v[4], w1v[4];
; #pragma unroll
;             for (int j = 0; j < 4; ++j) { const int row = rowc + jb + j; rs4v[j] = *(const f32x4*)(rowss + (size_t)row * 4); w0v[j] = *(const u32x4*)(H + (size_t)row * DM + 16 * lane); w1v[j] = *(const u32x4*)(H + (size_t)row * DM + 16 * lane + 8); }
.LBB0_480:
	v_readlane_b32 s0, v252, 24
	v_lshlrev_b32_e32 v0, 10, v188
	s_waitcnt vmcnt(0)
	v_lshlrev_b32_e32 v2, 2, v188
	v_ashrrev_i32_e32 v189, 31, v188
	v_readlane_b32 s1, v252, 25
	v_and_b32_e32 v0, 0xc00, v0
	v_and_b32_e32 v2, 0x3f0, v2
	s_waitcnt lgkmcnt(0)
	v_lshl_add_u64 v[190:191], v[188:189], 4, s[0:1]
	v_add3_u32 v0, 0, v0, v2
	v_and_b32_e32 v18, 0xfffff00, v188
	v_lshl_add_u32 v209, v18, 4, v0
	v_add_u32_e32 v18, 0x200, v188
	v_and_b32_e32 v18, 0xfffff00, v18
	v_lshl_add_u32 v210, v18, 4, v0
	v_add_u32_e32 v18, 0x400, v188
	v_and_b32_e32 v18, 0xfffff00, v18
	v_lshl_add_u32 v211, v18, 4, v0
	v_add_u32_e32 v18, 0x600, v188
	v_and_b32_e32 v18, 0xfffff00, v18
	v_lshl_add_u32 v213, v18, 4, v0
	v_readlane_b32 s0, v252, 26
	v_ashrrev_i32_e32 v0, 6, v188
	v_mov_b32_e32 v212, v248
	v_and_b32_e32 v208, 63, v188
	v_bfe_u32 v2, v188, 3, 3
	v_or_b32_e32 v2, s0, v2
	v_readlane_b32 s0, v249, 3
	v_ashrrev_i32_e32 v3, 31, v2
	v_lshl_add_u64 v[192:193], v[2:3], 2, s[74:75]
	v_readlane_b32 s1, v251, 11
	s_cmp_lg_u32 s1, 0x4000
	s_cbranch_scc1 .Lfg_nomap
	s_lshr_b32 s1, s0, 3
	s_and_b32 s0, s1, 7
	s_lshl_b32 s0, s0, 8
	s_andn2_b32 s1, s1, 7
	s_add_i32 s0, s0, s1
.Lfg_nomap:
	v_add_u32_e32 v189, s0, v0
	s_movk_i32 s0, 0x800
	v_cmp_gt_i32_e64 s[0:1], s0, v189
	v_readlane_b32 s2, v252, 32
	v_readlane_b32 s3, v252, 33
	v_readlane_b32 s4, v249, 61
	v_readlane_b32 s5, v249, 62
	s_mov_b32 s30, 0xcccccccc
	s_mov_b32 s31, 0xcccccccc
	s_mov_b32 s40, 0xaaaaaaaa
	s_mov_b32 s41, 0xaaaaaaaa
	v_lshlrev_b32_e32 v184, 14, v189
	v_lshl_add_u32 v184, v208, 5, v184
	v_lshrrev_b32_e32 v215, 8, v189
	v_mul_u32_u24_e32 v215, 0x6000, v215
	v_lshl_add_u32 v215, v208, 6, v215
	v_and_b32_e32 v216, 7, v208
	v_lshlrev_b32_e32 v217, 7, v189
	v_lshl_add_u32 v217, v216, 4, v217
	v_lshlrev_b32_e32 v246, 8, v189
	v_lshl_add_u32 v246, v216, 5, v246
	v_lshrrev_b32_e32 v216, 3, v208
	v_lshl_add_u32 v246, v216, 2, v246
	s_mov_b64 s[6:7], 0x2000
	v_lshl_add_u64 v[18:19], v[190:191], 0, s[6:7]
	s_mov_b64 s[6:7], 0x4000
	v_lshl_add_u64 v[20:21], v[190:191], 0, s[6:7]
	s_mov_b64 s[6:7], 0x6000
	v_lshl_add_u64 v[22:23], v[190:191], 0, s[6:7]
	global_load_dwordx4 v[2:5], v[190:191], off
	global_load_dwordx4 v[6:9], v[18:19], off
	global_load_dwordx4 v[10:13], v[20:21], off
	global_load_dwordx4 v[14:17], v[22:23], off
	s_and_saveexec_b64 s[38:39], s[0:1]
	global_load_dword v214, v[192:193], off
	global_load_dwordx4 v[130:133], v215, s[2:3]
	global_load_dwordx4 v[134:137], v215, s[2:3] offset:16
	global_load_dwordx4 v[138:141], v215, s[2:3] offset:32
	global_load_dwordx4 v[142:145], v215, s[2:3] offset:48
	global_load_dwordx4 v[178:181], v217, s[34:35]
	global_load_dwordx4 v[146:149], v184, s[94:95]
	global_load_dwordx4 v[150:153], v184, s[94:95] offset:16
	global_load_dwordx4 v[154:157], v184, s[94:95] offset:2048
	global_load_dwordx4 v[158:161], v184, s[94:95] offset:2064
	v_add_u32_e32 v184, 0x1000, v184
	global_load_dwordx4 v[162:165], v184, s[94:95]
	global_load_dwordx4 v[166:169], v184, s[94:95] offset:16
	global_load_dwordx4 v[170:173], v184, s[94:95] offset:2048
	global_load_dwordx4 v[174:177], v184, s[94:95] offset:2064
	v_add_u32_e32 v184, 0x1000, v184
	s_or_b64 exec, exec, s[38:39]
	s_cmp_lg_u64 s[0:1], 0
	s_cbranch_scc1 .Lfg_wv
	s_waitcnt vmcnt(0)
	s_branch .Lfg_wd

; __device__ __forceinline__ unsigned xb_add(unsigned* p, unsigned v) { return __hip_atomic_fetch_add(p, v, __ATOMIC_RELAXED, __HIP_MEMORY_SCOPE_AGENT); }
; __device__ __forceinline__ void xcd_barrier(const XcdBarrier& b, const int tid) {
;     asm volatile("s_waitcnt vmcnt(0)" ::: "memory");
;     __syncthreads();
;     if (tid == 0) {
;         unsigned* bar = b.bar;
;         __builtin_amdgcn_s_waitcnt(0);
;         unsigned nloc = b.st[0], nx = b.st[1];
;         if (nloc == 0u) { xcd_barrier_complete(bar, b.x, nloc, nx); b.st[0] = nloc; b.st[1] = nx; }
;         const unsigned old = xb_add(&bar[XB_XSUB(b.x)], 1u);
;         const unsigned gen = old / nloc;
;         if (old + 1u == (gen + 1u) * nloc) {
.LBB0_570:
	s_and_b64 vcc, exec, s[0:1]
	s_cbranch_vccz .LBB0_623
	s_waitcnt vmcnt(0)
	s_waitcnt vmcnt(0) lgkmcnt(0)
	s_barrier
	s_mov_b64 s[0:1], exec
	v_readlane_b32 s2, v251, 38
	v_readlane_b32 s3, v251, 39
	s_and_b64 s[2:3], s[0:1], s[2:3]
	s_mov_b64 exec, s[2:3]
	s_cbranch_execz .LBB0_622
	s_mov_b32 s99, 0
	s_cmp_eq_u32 s48, 1
	s_cbranch_scc0 .Lxb_nf1
	v_writelane_b32 v255, s99, 21
	v_readlane_b32 s5, v249, 0
	s_cmp_lt_u32 s5, 8
	s_cbranch_scc0 .Lxb_md
	s_getreg_b32 s4, hwreg(HW_REG_XCC_ID, 0, 4)
	s_add_i32 s4, s4, 1
	v_mov_b32_e32 v4, s4
	s_lshl_b32 s5, s5, 2
	v_mov_b32_e32 v5, s5
	v_readlane_b32 s4, v252, 12
	v_readlane_b32 s5, v252, 13
	s_nop 4
	global_store_dword v5, v4, s[4:5] offset:2064 sc1
	s_waitcnt vmcnt(0)
	s_branch .Lxb_md
.Lxb_nf1:
	s_cmp_eq_u32 s48, 2
	s_cbranch_scc0 .Lxb_nf2
	v_readlane_b32 s5, v249, 0
	s_and_b32 s5, s5, 7
	s_lshl_b32 s5, s5, 2
	v_mov_b32_e32 v5, s5
	v_readlane_b32 s4, v252, 12
	v_readlane_b32 s5, v252, 13
	s_nop 4
	global_load_dword v4, v5, s[4:5] offset:2064 sc1
	s_waitcnt vmcnt(0)
	v_readfirstlane_b32 s4, v4
	s_getreg_b32 s5, hwreg(HW_REG_XCC_ID, 0, 4)
	s_add_i32 s5, s5, 1
	s_cmp_eq_u32 s4, s5
	s_cbranch_scc1 .Lxb_md
	v_readlane_b32 s4, v252, 12
	v_readlane_b32 s5, v252, 13
	v_mov_b32_e32 v4, 1
	s_nop 4
	global_atomic_add v1, v4, s[4:5] offset:2052
	s_waitcnt vmcnt(0)
	s_branch .Lxb_md
.Lxb_nf2:
	s_cmp_eq_u32 s48, 3
	s_cbranch_scc0 .Lxb_nf3
	v_readlane_b32 s4, v252, 12
	v_readlane_b32 s5, v252, 13
	s_nop 4
	global_load_dword v4, v1, s[4:5] offset:2052 sc1
	v_readlane_b32 s5, v251, 11
	s_waitcnt vmcnt(0)
	v_readfirstlane_b32 s4, v4
	s_cmp_eq_u32 s4, 0
	s_cselect_b32 s4, 1, 0
	s_cmp_eq_u32 s5, 0x4000
	s_cselect_b32 s4, s4, 0
	s_nop 1
	v_writelane_b32 v255, s4, 21
	s_nop 1
.Lxb_nf3:
	s_movk_i32 s4, 0xd68
	s_lshr_b32 s4, s4, s48
	v_readlane_b32 s5, v255, 21
	s_and_b32 s4, s4, 1
	s_and_b32 s99, s4, s5
.Lxb_md:
	v_readlane_b32 s2, v251, 34
	s_waitcnt vmcnt(0) expcnt(0) lgkmcnt(0)
	s_nop 0
	v_mov_b32_e32 v0, s2
	ds_read_b32 v3, v0
	v_readlane_b32 s2, v251, 35
	s_waitcnt lgkmcnt(0)
	v_cmp_ne_u32_e32 vcc, 0, v3
	v_mov_b32_e32 v0, s2
	ds_read_b32 v2, v0
	s_cbranch_vccnz .LBB0_586
	s_mov_b32 s7, 0
	s_branch .LBB0_575

; __device__ __forceinline__ unsigned xb_ld(unsigned* p)              { return __hip_atomic_load(p, __ATOMIC_RELAXED, __HIP_MEMORY_SCOPE_AGENT); }
; __device__ __forceinline__ unsigned xb_add(unsigned* p, unsigned v) { return __hip_atomic_fetch_add(p, v, __ATOMIC_RELAXED, __HIP_MEMORY_SCOPE_AGENT); }
; #define XB_SPIN(cond, bar) do { unsigned _sp = 0; while (cond) { __builtin_amdgcn_s_sleep(1); \
;     if ((++_sp & 255u) == 0u) { if (xb_ld(&(bar)[XB_TMO])) break; if (_sp > XB_SPIN_CAP) { atomicAdd(&(bar)[XB_TMO], 1u); break; } } } } while (0)
; __device__ __forceinline__ void xcd_barrier(const XcdBarrier& b, const int tid) {
;     ...
;         const unsigned old = xb_add(&bar[XB_XSUB(b.x)], 1u);
;         const unsigned gen = old / nloc;
;         if (old + 1u == (gen + 1u) * nloc) {
;             __builtin_amdgcn_fence(__ATOMIC_RELEASE, "agent");
;             asm volatile("s_waitcnt vmcnt(0)" ::: "memory");
;             const unsigned og = xb_add(&bar[XB_TOP], 1u);
;             const unsigned tg = og / nx;
;             if (og + 1u == (tg + 1u) * nx) xb_add(&bar[XB_TOPGEN], 1u);
;             else XB_SPIN(xb_ld(&bar[XB_TOPGEN]) == tg, bar);
;             __builtin_amdgcn_fence(__ATOMIC_ACQUIRE, "agent");
;             xb_add(&bar[XB_XGEN(b.x)], 1u);
;             asm volatile("s_waitcnt vmcnt(0)" ::: "memory");
.LBB0_602:
	s_andn2_saveexec_b64 s[2:3], s[2:3]
	s_cbranch_execz .LBB0_622
	s_mov_b64 s[2:3], exec
	s_cmp_eq_u32 s99, 1
	s_cbranch_scc0 .Lxb_glob
	v_readlane_b32 s4, v250, 11
	v_readlane_b32 s5, v250, 12
	v_mov_b32_e32 v4, 1
	s_nop 4
	global_atomic_add v1, v4, s[4:5]
	s_mov_b64 s[4:5], 0
	s_branch .LBB0_617
.Lxb_glob:
	buffer_wbl2 sc1
	s_waitcnt lgkmcnt(0)
	s_waitcnt vmcnt(0)
	v_mbcnt_lo_u32_b32 v0, s2, 0
	v_mbcnt_hi_u32_b32 v0, s3, v0
	v_cmp_eq_u32_e32 vcc, 0, v0
	s_and_saveexec_b64 s[4:5], vcc
	s_cbranch_execz .LBB0_605
	s_bcnt1_i32_b64 s2, s[2:3]
	v_mov_b32_e32 v3, s2
	v_readlane_b32 s2, v250, 13
	v_readlane_b32 s3, v250, 14
	s_nop 4
	global_atomic_add v3, v1, v3, s[2:3] sc0
